# v021
# speedup vs baseline: 1.0061x; 1.0061x over previous
.LBB0_174:
	s_mov_b32 s7, s81
	v_writelane_b32 v255, s6, 58
	s_and_b32 s2, s6, 1
	s_cmp_eq_u32 s2, 0
	s_cselect_b64 s[10:11], -1, 0
	s_cmp_eq_u32 s2, 1
	v_readlane_b32 s2, v253, 33
	v_mov_b32_e32 v0, v195
	v_readlane_b32 s3, v253, 34
	v_writelane_b32 v255, s7, 59
	s_cselect_b64 s[38:39], -1, 0
	s_andn2_b64 vcc, exec, s[2:3]
	v_readfirstlane_b32 s12, v0
	s_cbranch_vccnz .LBB0_231
	s_mov_b32 s100, 0
	s_mov_b32 s101, -1
	v_lshlrev_b32_e32 v2, 4, v0
	v_add_u32_e32 v3, 0x2000, v2
	v_ashrrev_i32_e32 v4, 31, v3
	v_lshrrev_b32_e32 v4, 22, v4
	v_add_u32_e32 v4, v3, v4
	v_ashrrev_i32_e32 v6, 10, v4
	v_mul_i32_i24_e32 v4, 0x400, v6
	v_sub_u32_e32 v3, v3, v4
	v_lshrrev_b32_e32 v4, 4, v3
	v_writelane_b32 v255, s38, 60
	v_bitop3_b32 v3, v4, v3, 32 bitop3:0x6c
	v_ashrrev_i32_e32 v4, 31, v3
	v_writelane_b32 v255, s39, 61
	v_lshrrev_b32_e32 v4, 26, v4
	v_readlane_b32 s14, v255, 58
	v_readlane_b32 s15, v255, 59
	v_add_u32_e32 v4, v3, v4
	s_waitcnt vmcnt(26)
	v_lshlrev_b32_e32 v5, 3, v6
	s_lshl_b64 s[2:3], s[14:15], 25
	v_readlane_b32 s5, v253, 31
	s_waitcnt vmcnt(24)
	v_ashrrev_i32_e32 v7, 6, v4
	v_and_b32_e32 v5, -16, v5
	s_add_u32 s80, s5, s2
	v_readlane_b32 s2, v253, 32
	v_add_u32_e32 v5, v7, v5
	s_addc_u32 s24, s2, s3
	v_and_b32_e32 v8, 3, v7
	s_mov_b32 s3, 0xfffe0
	s_waitcnt vmcnt(22)
	v_lshrrev_b32_e32 v9, 2, v5
	v_lshlrev_b32_e32 v10, 1, v5
	v_and_b32_e32 v4, 0xc0, v4
	v_and_or_b32 v8, v5, s3, v8
	v_and_b32_e32 v9, 4, v9
	v_and_b32_e32 v10, 24, v10
	v_sub_u32_e32 v3, v3, v4
	s_waitcnt vmcnt(18)
	v_mov_b32_e32 v13, 1
	v_or3_b32 v9, v8, v9, v10
	v_lshlrev_b32_e32 v8, 5, v6
	v_ashrrev_i16_sdwa v3, v13, sext(v3) dst_sel:DWORD dst_unused:UNUSED_PAD src0_sel:DWORD src1_sel:BYTE_0
	v_and_b32_e32 v10, 32, v8
	v_bfe_i32 v8, v3, 0, 16
	v_add_lshl_u32 v3, v10, v8, 1
	v_lshl_add_u32 v130, v9, 12, v3
	v_lshl_add_u32 v132, v5, 12, v3
	v_bfe_i32 v3, v0, 27, 1
	v_lshrrev_b32_e32 v3, 22, v3
	v_add_u32_e32 v3, v2, v3
	v_and_b32_e32 v3, 0xfffffc00, v3
	v_sub_u32_e32 v2, v2, v3
	v_lshrrev_b32_e32 v3, 4, v2
	v_ashrrev_i32_e32 v4, 31, v0
	v_bitop3_b32 v2, v3, v2, 32 bitop3:0x6c
	v_lshrrev_b32_e32 v4, 26, v4
	v_ashrrev_i32_e32 v3, 31, v2
	v_add_u32_e32 v4, v0, v4
	v_lshrrev_b32_e32 v3, 26, v3
	v_ashrrev_i32_e32 v10, 6, v4
	v_add_u32_e32 v3, v2, v3
	v_lshlrev_b32_e32 v4, 3, v10
	v_ashrrev_i32_e32 v9, 6, v3
	v_and_b32_e32 v4, -16, v4
	v_add_u32_e32 v4, v9, v4
	v_and_b32_e32 v5, 3, v9
	v_lshrrev_b32_e32 v11, 2, v4
	v_lshlrev_b32_e32 v12, 1, v4
	v_and_b32_e32 v3, 0xc0, v3
	s_ashr_i32 s2, s12, 6
	v_and_or_b32 v5, v4, s3, v5
	v_and_b32_e32 v11, 4, v11
	v_and_b32_e32 v12, 24, v12
	v_sub_u32_e32 v2, v2, v3
	s_ashr_i32 s13, s12, 8
	s_lshl_b32 s25, s2, 10
	v_or3_b32 v5, v5, v11, v12
	v_lshlrev_b32_e32 v11, 5, v10
	v_ashrrev_i16_sdwa v2, v13, sext(v2) dst_sel:DWORD dst_unused:UNUSED_PAD src0_sel:DWORD src1_sel:BYTE_0
	v_readlane_b32 s6, v255, 0
	v_and_b32_e32 v12, 32, v11
	v_bfe_i32 v11, v2, 0, 16
	v_readlane_b32 s7, v255, 1
	s_add_u32 s48, s80, s6
	v_add_lshl_u32 v2, v12, v11, 1
	s_addc_u32 s49, s24, s7
	s_add_i32 s5, s25, 0
	v_lshl_add_u32 v134, v5, 12, v2
	s_add_i32 m0, s5, 0x10000
	v_lshl_add_u32 v136, v4, 12, v2
	global_load_lds_dwordx4 v134, s[48:49]
	s_add_i32 m0, s5, 0x12000
	s_add_u32 s8, s48, 0x80000
	global_load_lds_dwordx4 v130, s[48:49]
	s_addc_u32 s9, s49, 0
	s_add_i32 m0, s5, 0x14000
	s_add_i32 s7, s5, 0x2000
	global_load_lds_dwordx4 v134, s[8:9]
	s_add_i32 m0, s5, 0x16000
	s_add_i32 s82, s5, 0x4000
	global_load_lds_dwordx4 v130, s[8:9]
	v_readlane_b32 s8, v255, 5
	s_mov_b32 m0, s5
	v_readlane_b32 s9, v255, 6
	s_add_i32 s83, s5, 0x6000
	v_mov_b32_e32 v135, v1
	v_mov_b32_e32 v131, v1
	s_cmp_eq_u32 s13, 1
	v_lshl_add_u64 v[2:3], s[48:49], 0, v[134:135]
	global_load_lds_dwordx4 v136, s[8:9]
	s_mov_b32 m0, s7
	v_lshl_add_u64 v[4:5], s[48:49], 0, v[130:131]
	global_load_lds_dwordx4 v132, s[8:9]
	v_readlane_b32 s8, v255, 7
	s_mov_b32 m0, s82
	v_readlane_b32 s9, v255, 8
	s_nop 4
	global_load_lds_dwordx4 v136, s[8:9]
	s_mov_b32 m0, s83
	s_nop 0
	global_load_lds_dwordx4 v132, s[8:9]
	s_cselect_b64 s[8:9], -1, 0
	s_cmp_lg_u32 s13, 1
	s_cbranch_scc1 .LBB0_177
	s_barrier

.LBB0_186:
	s_cmp_eq_u32 s101, s78
	s_cbranch_scc0 .Lmy_rs_miss
	v_lshl_add_u32 v144, s78, 8, v139
	s_mov_b32 s6, 0xf800000
	s_cmp_lt_i32 s37, 16
	s_cselect_b64 s[22:23], -1, 0
	s_lshl_b32 s15, s37, 1
	s_mul_i32 s17, s37, 0xc00000
	s_mul_hi_i32 s15, s15, 0x600000
	v_mov_b32_e32 v153, 0
	s_mov_b32 s65, 0xf800000
	v_xor_b32_e32 v157, 32, v229
	s_and_b64 s[50:51], s[12:13], s[22:23]
	s_add_u32 s22, s63, s17
	s_addc_u32 s23, s4, s15
	v_mov_b32_e32 v159, 0
	v_and_b32_e32 v145, 64, v229
	v_xor_b32_e32 v0, 16, v229
	v_add_u32_e32 v154, 64, v145
	v_cmp_lt_i32_e32 vcc, v0, v154
	v_ashrrev_i32_e32 v145, 31, v144
	v_lshlrev_b64 v[148:149], 8, v[144:145]
	v_cndmask_b32_e32 v0, v229, v0, vcc
	v_lshlrev_b32_e32 v155, 2, v0
	v_mov_b32_e32 v156, v231
	v_mov_b32_e32 v158, v232
	v_mov_b32_e32 v163, v233
	v_mov_b32_e32 v160, v234
	v_mov_b32_e32 v166, v235
	v_mov_b32_e32 v167, v236
	v_mov_b32_e32 v164, v237
	v_mov_b32_e32 v165, v238
	s_waitcnt vmcnt(0)
	s_branch .Lmy_rs_join
.Lmy_rs_miss:
	v_lshl_add_u32 v144, s78, 8, v139
	v_add_u32_e32 v158, v151, v144
	v_ashrrev_i32_e32 v159, 31, v158
	v_readlane_b32 s50, v253, 27
	v_lshlrev_b64 v[146:147], 5, v[158:159]
	v_readlane_b32 s51, v253, 28
	s_mov_b32 s6, 0xf800000
	s_cmp_lt_i32 s37, 16
	v_lshl_add_u64 v[154:155], s[50:51], 0, v[146:147]
	global_load_dwordx4 v[146:149], v[154:155], off
	s_nop 0
	global_load_dwordx4 v[154:157], v[154:155], off offset:16
	s_cselect_b64 s[22:23], -1, 0
	s_lshl_b32 s15, s37, 1
	s_mul_i32 s17, s37, 0xc00000
	s_mul_hi_i32 s15, s15, 0x600000
	v_mov_b32_e32 v153, 0
	s_mov_b32 s65, 0xf800000
	s_waitcnt vmcnt(0)
	v_mov_b32_e32 v160, v146
	v_mov_b32_e32 v161, v154
	v_mov_b32_e32 v154, v147
	v_pk_add_f32 v[146:147], v[160:161], v[154:155]
	v_mov_b32_e32 v154, v148
	v_mov_b32_e32 v155, v156
	v_mov_b32_e32 v156, v149
	v_pk_add_f32 v[148:149], v[154:155], v[156:157]
	v_xor_b32_e32 v157, 32, v229
	v_pk_add_f32 v[146:147], v[146:147], v[148:149]
	s_nop 0
	v_add_f32_e32 v0, 0, v146
	v_add_f32_e32 v0, v0, v147
	v_fmamk_f32 v0, v0, 0x3a000000, v226
	v_cmp_gt_f32_e32 vcc, s6, v0
	v_mul_f32_e32 v145, 0x4f800000, v0
	s_nop 0
	v_cndmask_b32_e32 v0, v0, v145, vcc
	v_sqrt_f32_e32 v145, v0
	s_nop 0
	v_add_u32_e32 v146, -1, v145
	v_fma_f32 v147, -v146, v145, v0
	v_cmp_ge_f32_e64 s[48:49], 0, v147
	v_add_u32_e32 v147, 1, v145
	s_nop 0
	v_cndmask_b32_e64 v146, v145, v146, s[48:49]
	v_fma_f32 v145, -v147, v145, v0
	v_cmp_lt_f32_e64 s[48:49], 0, v145
	s_nop 1
	v_cndmask_b32_e64 v145, v146, v147, s[48:49]
	v_mul_f32_e32 v146, 0x37800000, v145
	v_cndmask_b32_e32 v145, v145, v146, vcc
	v_cmp_class_f32_e32 vcc, v0, v227
	s_nop 1
	v_cndmask_b32_e32 v0, v145, v0, vcc
	v_div_scale_f32 v145, s[48:49], v0, v0, 1.0
	v_rcp_f32_e32 v146, v145
	s_nop 0
	v_fma_f32 v147, -v145, v146, 1.0
	v_fmac_f32_e32 v146, v147, v146
	v_div_scale_f32 v147, vcc, 1.0, v0, 1.0
	v_mul_f32_e32 v148, v147, v146
	v_fma_f32 v149, -v145, v148, v147
	v_fmac_f32_e32 v148, v149, v146
	v_fma_f32 v145, -v145, v148, v147
	v_div_fmas_f32 v145, v145, v146, v148
	v_or_b32_e32 v146, 16, v158
	v_ashrrev_i32_e32 v147, 31, v146
	v_lshlrev_b64 v[146:147], 5, v[146:147]
	v_lshl_add_u64 v[154:155], s[50:51], 0, v[146:147]
	global_load_dwordx4 v[146:149], v[154:155], off offset:16
	global_load_dwordx4 v[158:161], v[154:155], off
	v_div_fixup_f32 v156, v145, v0, 1.0
	s_and_b64 s[50:51], s[12:13], s[22:23]
	s_add_u32 s22, s63, s17
	s_addc_u32 s23, s4, s15
	s_waitcnt vmcnt(0)
	v_add_f32_e32 v0, v158, v159
	v_add_f32_e32 v145, v160, v161
	v_add_f32_e32 v0, v0, v145
	v_add_f32_e32 v145, v146, v147
	v_add_f32_e32 v146, v148, v149
	v_add_f32_e32 v0, 0, v0
	v_add_f32_e32 v145, v145, v146
	v_add_f32_e32 v0, v0, v145
	v_fmamk_f32 v0, v0, 0x3a000000, v226
	v_cmp_gt_f32_e32 vcc, s6, v0
	v_mul_f32_e32 v145, 0x4f800000, v0
	v_mov_b32_e32 v159, 0
	v_cndmask_b32_e32 v0, v0, v145, vcc
	v_sqrt_f32_e32 v145, v0
	s_nop 0
	v_add_u32_e32 v146, -1, v145
	v_fma_f32 v147, -v146, v145, v0
	v_cmp_ge_f32_e64 s[48:49], 0, v147
	v_add_u32_e32 v147, 1, v145
	s_nop 0
	v_cndmask_b32_e64 v146, v145, v146, s[48:49]
	v_fma_f32 v145, -v147, v145, v0
	v_cmp_lt_f32_e64 s[48:49], 0, v145
	s_nop 1
	v_cndmask_b32_e64 v145, v146, v147, s[48:49]
	v_mul_f32_e32 v146, 0x37800000, v145
	v_cndmask_b32_e32 v145, v145, v146, vcc
	v_cmp_class_f32_e32 vcc, v0, v227
	s_nop 1
	v_cndmask_b32_e32 v0, v145, v0, vcc
	v_div_scale_f32 v145, s[48:49], v0, v0, 1.0
	v_rcp_f32_e32 v146, v145
	s_nop 0
	v_fma_f32 v147, -v145, v146, 1.0
	v_fmac_f32_e32 v146, v147, v146
	v_div_scale_f32 v147, vcc, 1.0, v0, 1.0
	v_mul_f32_e32 v148, v147, v146
	v_fma_f32 v149, -v145, v148, v147
	v_fmac_f32_e32 v148, v149, v146
	v_fma_f32 v145, -v145, v148, v147
	v_div_fmas_f32 v145, v145, v146, v148
	v_div_fixup_f32 v158, v145, v0, 1.0
	v_mov_b32_e32 v0, v156
	v_mov_b32_e32 v145, v156
	s_nop 1
	v_permlane32_swap_b32_e32 v0, v145
	v_cndmask_b32_e64 v163, v145, v0, s[38:39]
	v_mov_b32_e32 v0, v158
	v_mov_b32_e32 v145, v158
	s_nop 1
	v_permlane32_swap_b32_e32 v0, v145
	v_cndmask_b32_e64 v160, v145, v0, s[38:39]
	v_and_b32_e32 v145, 64, v229
	v_xor_b32_e32 v0, 16, v229
	v_add_u32_e32 v154, 64, v145
	v_cmp_lt_i32_e32 vcc, v0, v154
	v_ashrrev_i32_e32 v145, 31, v144
	v_lshlrev_b64 v[148:149], 8, v[144:145]
	v_cndmask_b32_e32 v0, v229, v0, vcc
	v_lshlrev_b32_e32 v155, 2, v0
	ds_bpermute_b32 v166, v155, v156
	ds_bpermute_b32 v167, v155, v163
	ds_bpermute_b32 v164, v155, v158
	ds_bpermute_b32 v165, v155, v160
	s_waitcnt lgkmcnt(0)
	v_mov_b32_e32 v231, v156
	v_mov_b32_e32 v232, v158
	v_mov_b32_e32 v233, v163
	v_mov_b32_e32 v234, v160
	v_mov_b32_e32 v235, v166
	v_mov_b32_e32 v236, v167
	v_mov_b32_e32 v237, v164
	v_mov_b32_e32 v238, v165
	s_mov_b32 s101, s78
.Lmy_rs_join:
	v_lshl_add_u64 v[148:149], s[22:23], 0, v[148:149]
	s_waitcnt lgkmcnt(3)
	v_cndmask_b32_e64 v161, v166, v156, s[42:43]
	s_waitcnt lgkmcnt(2)
	v_cndmask_b32_e64 v162, v167, v163, s[42:43]
	v_cndmask_b32_e64 v146, v162, v161, s[40:41]
	v_lshlrev_b32_e32 v0, 1, v138
	v_pk_mul_f32 v[128:129], v[128:129], v[146:147] op_sel_hi:[1,0]
	v_pk_mul_f32 v[126:127], v[126:127], v[146:147] op_sel_hi:[1,0]
	v_pk_mul_f32 v[124:125], v[124:125], v[146:147] op_sel_hi:[1,0]
	v_pk_mul_f32 v[122:123], v[122:123], v[146:147] op_sel_hi:[1,0]
	v_cndmask_b32_e64 v147, 0, 1, s[50:51]
	v_lshl_add_u64 v[148:149], v[148:149], 0, v[0:1]
	v_cvt_pk_bf16_f32 v168, v126, v127
	v_cvt_pk_bf16_f32 v169, v128, v129
	v_cvt_pk_bf16_f32 v170, v122, v123
	v_cvt_pk_bf16_f32 v171, v124, v125
	v_cmp_ne_u32_e64 s[48:49], 1, v147
	s_andn2_b64 vcc, exec, s[50:51]
	v_cmp_lt_i32_e64 s[50:51], v157, v154
	global_store_dwordx4 v[148:149], v[168:171], off
	s_cbranch_vccnz .LBB0_188
	v_pk_mul_f32 v[128:129], v[128:129], v[128:129]
	v_pk_mul_f32 v[126:127], v[126:127], v[126:127]
	v_pk_mul_f32 v[124:125], v[124:125], v[124:125]
	v_pk_mov_b32 v[168:169], v[126:127], v[128:129] op_sel:[1,0]
	v_mov_b32_e32 v127, v129
	v_pk_mul_f32 v[122:123], v[122:123], v[122:123]
	v_pk_add_f32 v[126:127], v[168:169], v[126:127]
	v_mov_b32_e32 v128, v124
	v_mov_b32_e32 v129, v122
	v_mov_b32_e32 v122, v125
	v_pk_add_f32 v[122:123], v[128:129], v[122:123]
	v_add_f32_e32 v124, v126, v127
	v_add_f32_e32 v123, v123, v124
	v_add_f32_e32 v122, v122, v123
	ds_bpermute_b32 v123, v155, v122
	s_waitcnt lgkmcnt(0)
	v_add_f32_e32 v122, v122, v123
	v_cndmask_b32_e64 v123, v229, v157, s[50:51]
	v_lshlrev_b32_e32 v123, 2, v123
	ds_bpermute_b32 v123, v123, v122
	s_waitcnt lgkmcnt(0)
	v_add_f32_e32 v122, v122, v123
	v_max_f32_e32 v159, 0, v122
